# v43 plus QKV K-loop: the compiler's vmcnt(0) drain at the top of every iteration removed from the steady-state loop body (kept in the peeled first iteration)
# baseline (speedup 1.0000x reference)
; #define PG8_STAGE(bufoff, gbase, voff) do { _Pragma("unroll") for (int _i = 0; _i < 2; ++_i) \
;         __builtin_amdgcn_global_load_lds((const unsigned*)((const char*)(gbase) + (voff)[_i]), (PG8_LAS unsigned*)(lds + (bufoff) + ldsw + _i * 8192), 16, 0, 0); } while (0)
; #define PG8_LDA(dst, b, h) do { _Pragma("unroll") for (int m = 0; m < 4; ++m) _Pragma("unroll") for (int k = 0; k < 2; ++k) dst[m][k] = *(const PG8_LAS bf16x8*)(lds + PG8_SA(b, h) + aoff + m * 2048 + k * 1024); } while (0)
; #define PG8_LDB(dst, b, h) do { _Pragma("unroll") for (int n = 0; n < 2; ++n) _Pragma("unroll") for (int k = 0; k < 2; ++k) dst[n][k] = *(const PG8_LAS bf16x8*)(lds + PG8_SB(b, h) + boff + n * 2048 + k * 1024); } while (0)
; #define PG8_MMA(ai, bj, At, Bt) do { __builtin_amdgcn_s_setprio(1); _Pragma("unroll") for (int m = 0; m < 4; ++m) _Pragma("unroll") for (int n = 0; n < 2; ++n) _Pragma("unroll") for (int k = 0; k < 2; ++k) \
;         acc[ai][bj][m][n] = mma16<Epi::I8>(Bt[n][k], At[m][k], acc[ai][bj][m][n]); __builtin_amdgcn_s_setprio(0); } while (0)
; #define PG8_WAIT_V(n) asm volatile("s_waitcnt vmcnt(" #n ")" ::: "memory")
; template <class Epi, class Sched, bool ALIGN_EPI = false, bool SP2 = false>
; __device__ __forceinline__ void gemm_phase(PG8_LAS unsigned char* lds, const Gemm g, const Sched& S, const Epi& E) {
;     ...
;             PG8_LDB(B0, 0, 0); PG8_LDB(B1, 0, 1); PG8_SCHED; PG8_LDA(At, 0, 0); PG8_STAGE(PG8_SA(1, 1), a1 + hstep, voffA);
;             PG8_WAIT_V(8); PG8_WAIT_L(0); PG8_BAR; PG8_MMA(0, 0, At, B0); PG8_MMA(0, 1, At, B1); PG8_BAR; PG8_SCHED;
;             PG8_LDA(At, 0, 1); PG8_STAGE(PG8_SB(0, 0), b2, voffB); PG8_STAGE(PG8_SB(0, 1), b2 + hstep, voffB); PG8_STAGE(PG8_SA(0, 0), a2, voffA);
;             PG8_WAIT_V(8); PG8_WAIT_L(0); PG8_BAR; PG8_MMA(1, 0, At, B0); PG8_MMA(1, 1, At, B1); PG8_BAR; PG8_SCHED;
;             PG8_LDB(B0, 1, 0); PG8_LDB(B1, 1, 1); PG8_SCHED; PG8_LDA(At, 1, 0); PG8_STAGE(PG8_SA(0, 1), a2 + hstep, voffA);
;             PG8_WAIT_V(8); PG8_WAIT_L(0); PG8_BAR; PG8_MMA(0, 0, At, B0); PG8_MMA(0, 1, At, B1); PG8_BAR; PG8_SCHED;
;             PG8_LDA(At, 1, 1); PG8_STAGE(PG8_SB(1, 0), b3, voffB); PG8_STAGE(PG8_SB(1, 1), b3 + hstep, voffB); PG8_STAGE(PG8_SA(1, 0), a3, voffA);
;             PG8_WAIT_V(8); PG8_WAIT_L(0); PG8_BAR; PG8_MMA(1, 0, At, B0); PG8_MMA(1, 1, At, B1); PG8_BAR; PG8_SCHED;
.LBB0_291:
	s_add_u32 s84, s8, 0x100
	s_addc_u32 s85, s9, 0
	s_add_i32 s66, 0, 0x10000
	s_cmp_eq_u32 s10, 12
	s_cselect_b32 vcc_hi, s5, s85
	s_cselect_b32 vcc_lo, s7, s84
	s_cselect_b32 s97, s11, s68
	s_cselect_b32 s96, s67, s69
	s_add_i32 s70, 0, 0x14000
	v_add_u32_e32 v110, s66, v175
	v_add_u32_e32 v168, s70, v175
	ds_read_b128 v[66:69], v110
	ds_read_b128 v[70:73], v110 offset:1024
	ds_read_b128 v[106:109], v110 offset:2048
	ds_read_b128 v[110:113], v110 offset:3072
	ds_read_b128 v[114:117], v168
	ds_read_b128 v[118:121], v168 offset:1024
	ds_read_b128 v[126:129], v168 offset:2048
	ds_read_b128 v[178:181], v168 offset:3072
	v_lshl_add_u64 v[168:169], s[8:9], 0, v[164:165]
	s_add_i32 m0, s1, 0xc000
	ds_read_b128 v[182:185], v177
	ds_read_b128 v[186:189], v177 offset:1024
	ds_read_b128 v[190:193], v177 offset:2048
	ds_read_b128 v[194:197], v177 offset:3072
	ds_read_b128 v[198:201], v177 offset:4096
	ds_read_b128 v[210:213], v177 offset:5120
	ds_read_b128 v[214:217], v177 offset:6144
	ds_read_b128 v[218:221], v177 offset:7168
	global_load_lds_dwordx4 v[168:169], off
	v_lshl_add_u64 v[168:169], s[8:9], 0, v[166:167]
	s_add_i32 m0, s1, 0xe000
	s_nop 0
	global_load_lds_dwordx4 v[168:169], off
	s_waitcnt vmcnt(8)
	s_waitcnt lgkmcnt(0)
	s_barrier
	s_setprio 1
	s_waitcnt lgkmcnt(0)
	v_mfma_i32_16x16x64_i8 v[154:157], v[66:69], v[182:185], v[154:157]
	v_mfma_i32_16x16x64_i8 v[146:149], v[106:109], v[182:185], v[146:149]
	v_mfma_i32_16x16x64_i8 v[138:141], v[106:109], v[190:193], v[138:141]
	v_mfma_i32_16x16x64_i8 v[150:153], v[66:69], v[190:193], v[150:153]
	v_mfma_i32_16x16x64_i8 v[142:145], v[66:69], v[198:201], v[142:145]
	v_mfma_i32_16x16x64_i8 v[130:133], v[106:109], v[198:201], v[130:133]
	v_mfma_i32_16x16x64_i8 v[122:125], v[106:109], v[214:217], v[122:125]
	v_mfma_i32_16x16x64_i8 v[134:137], v[66:69], v[214:217], v[134:137]
	v_mfma_i32_16x16x64_i8 v[154:157], v[70:73], v[186:189], v[154:157]
	v_mfma_i32_16x16x64_i8 v[146:149], v[110:113], v[186:189], v[146:149]
	v_mfma_i32_16x16x64_i8 v[138:141], v[110:113], v[194:197], v[138:141]
	v_mfma_i32_16x16x64_i8 v[150:153], v[70:73], v[194:197], v[150:153]
	v_mfma_i32_16x16x64_i8 v[142:145], v[70:73], v[210:213], v[142:145]
	v_mfma_i32_16x16x64_i8 v[130:133], v[110:113], v[210:213], v[130:133]
	v_mfma_i32_16x16x64_i8 v[122:125], v[110:113], v[218:221], v[122:125]
	v_mfma_i32_16x16x64_i8 v[134:137], v[70:73], v[218:221], v[134:137]
	s_setprio 0
	s_setprio 1
	v_mfma_i32_16x16x64_i8 v[102:105], v[114:117], v[182:185], v[102:105]
	v_mfma_i32_16x16x64_i8 v[94:97], v[126:129], v[182:185], v[94:97]
	v_mfma_i32_16x16x64_i8 v[86:89], v[126:129], v[190:193], v[86:89]
	v_mfma_i32_16x16x64_i8 v[98:101], v[114:117], v[190:193], v[98:101]
	v_mfma_i32_16x16x64_i8 v[90:93], v[114:117], v[198:201], v[90:93]
	v_mfma_i32_16x16x64_i8 v[78:81], v[126:129], v[198:201], v[78:81]
	v_mfma_i32_16x16x64_i8 v[74:77], v[126:129], v[214:217], v[74:77]
	v_mfma_i32_16x16x64_i8 v[82:85], v[114:117], v[214:217], v[82:85]
	v_mfma_i32_16x16x64_i8 v[102:105], v[118:121], v[186:189], v[102:105]
	v_mfma_i32_16x16x64_i8 v[94:97], v[178:181], v[186:189], v[94:97]
	v_mfma_i32_16x16x64_i8 v[86:89], v[178:181], v[194:197], v[86:89]
	v_mfma_i32_16x16x64_i8 v[98:101], v[118:121], v[194:197], v[98:101]
	v_mfma_i32_16x16x64_i8 v[90:93], v[118:121], v[210:213], v[90:93]
	v_mfma_i32_16x16x64_i8 v[78:81], v[178:181], v[210:213], v[78:81]
	v_mfma_i32_16x16x64_i8 v[74:77], v[178:181], v[218:221], v[74:77]
	v_mfma_i32_16x16x64_i8 v[82:85], v[118:121], v[218:221], v[82:85]
	s_setprio 0
	s_barrier
	s_add_i32 s8, s66, s81
	v_lshl_add_u64 v[168:169], s[96:97], 0, v[0:1]
	s_mov_b32 m0, s8
	ds_read_b128 v[182:185], v177 offset:16384
	ds_read_b128 v[186:189], v177 offset:17408
	ds_read_b128 v[190:193], v177 offset:18432
	ds_read_b128 v[194:197], v177 offset:19456
	ds_read_b128 v[198:201], v177 offset:20480
	ds_read_b128 v[210:213], v177 offset:21504
	ds_read_b128 v[214:217], v177 offset:22528
	ds_read_b128 v[218:221], v177 offset:23552
	global_load_lds_dwordx4 v[168:169], off
	s_add_i32 m0, s8, 0x2000
	s_add_u32 s8, s96, 0x40000
	v_lshl_add_u64 v[206:207], s[96:97], 0, v[158:159]
	s_addc_u32 s9, s97, 0
	s_add_i32 s66, s70, s81
	global_load_lds_dwordx4 v[206:207], off
	v_lshl_add_u64 v[222:223], s[8:9], 0, v[0:1]
	s_mov_b32 m0, s66
	v_lshl_add_u64 v[224:225], vcc, 0, v[160:161]
	global_load_lds_dwordx4 v[222:223], off
	v_lshl_add_u64 v[222:223], s[8:9], 0, v[158:159]
	s_add_i32 m0, s66, 0x2000
	s_nop 0
	global_load_lds_dwordx4 v[222:223], off
	v_lshl_add_u64 v[222:223], vcc, 0, v[162:163]
	s_mov_b32 m0, s1
	s_nop 0
	global_load_lds_dwordx4 v[222:223], off
	s_mov_b32 m0, s58
	s_nop 0
	global_load_lds_dwordx4 v[224:225], off
	s_waitcnt vmcnt(8)
	s_waitcnt lgkmcnt(0)
	s_barrier
; #define PG8_STAGE(bufoff, gbase, voff) do { _Pragma("unroll") for (int _i = 0; _i < 2; ++_i) \
;         __builtin_amdgcn_global_load_lds((const unsigned*)((const char*)(gbase) + (voff)[_i]), (PG8_LAS unsigned*)(lds + (bufoff) + ldsw + _i * 8192), 16, 0, 0); } while (0)
; #define PG8_LDA(dst, b, h) do { _Pragma("unroll") for (int m = 0; m < 4; ++m) _Pragma("unroll") for (int k = 0; k < 2; ++k) dst[m][k] = *(const PG8_LAS bf16x8*)(lds + PG8_SA(b, h) + aoff + m * 2048 + k * 1024); } while (0)
; #define PG8_LDB(dst, b, h) do { _Pragma("unroll") for (int n = 0; n < 2; ++n) _Pragma("unroll") for (int k = 0; k < 2; ++k) dst[n][k] = *(const PG8_LAS bf16x8*)(lds + PG8_SB(b, h) + boff + n * 2048 + k * 1024); } while (0)
; #define PG8_MMA(ai, bj, At, Bt) do { __builtin_amdgcn_s_setprio(1); _Pragma("unroll") for (int m = 0; m < 4; ++m) _Pragma("unroll") for (int n = 0; n < 2; ++n) _Pragma("unroll") for (int k = 0; k < 2; ++k) \
;         acc[ai][bj][m][n] = mma16<Epi::I8>(Bt[n][k], At[m][k], acc[ai][bj][m][n]); __builtin_amdgcn_s_setprio(0); } while (0)
; #define PG8_WAIT_V(n) asm volatile("s_waitcnt vmcnt(" #n ")" ::: "memory")
; template <class Epi, class Sched, bool ALIGN_EPI = false, bool SP2 = false>
; __device__ __forceinline__ void gemm_phase(PG8_LAS unsigned char* lds, const Gemm g, const Sched& S, const Epi& E) {
;     ...
;             PG8_LDB(B0, 0, 0); PG8_LDB(B1, 0, 1); PG8_SCHED; PG8_LDA(At, 0, 0); PG8_STAGE(PG8_SA(1, 1), a1 + hstep, voffA);
;             PG8_WAIT_V(8); PG8_WAIT_L(0); PG8_BAR; PG8_MMA(0, 0, At, B0); PG8_MMA(0, 1, At, B1); PG8_BAR; PG8_SCHED;
;             PG8_LDA(At, 0, 1); PG8_STAGE(PG8_SB(0, 0), b2, voffB); PG8_STAGE(PG8_SB(0, 1), b2 + hstep, voffB); PG8_STAGE(PG8_SA(0, 0), a2, voffA);
;             PG8_WAIT_V(8); PG8_WAIT_L(0); PG8_BAR; PG8_MMA(1, 0, At, B0); PG8_MMA(1, 1, At, B1); PG8_BAR; PG8_SCHED;
;             PG8_LDB(B0, 1, 0); PG8_LDB(B1, 1, 1); PG8_SCHED; PG8_LDA(At, 1, 0); PG8_STAGE(PG8_SA(0, 1), a2 + hstep, voffA);
;             PG8_WAIT_V(8); PG8_WAIT_L(0); PG8_BAR; PG8_MMA(0, 0, At, B0); PG8_MMA(0, 1, At, B1); PG8_BAR; PG8_SCHED;
;             PG8_LDA(At, 1, 1); PG8_STAGE(PG8_SB(1, 0), b3, voffB); PG8_STAGE(PG8_SB(1, 1), b3 + hstep, voffB); PG8_STAGE(PG8_SA(1, 0), a3, voffA);
;             PG8_WAIT_V(8); PG8_WAIT_L(0); PG8_BAR; PG8_MMA(1, 0, At, B0); PG8_MMA(1, 1, At, B1); PG8_BAR; PG8_SCHED;
	s_setprio 1
	s_waitcnt lgkmcnt(0)
	v_mfma_i32_16x16x64_i8 v[62:65], v[66:69], v[182:185], v[62:65]
	v_mfma_i32_16x16x64_i8 v[54:57], v[106:109], v[182:185], v[54:57]
	v_mfma_i32_16x16x64_i8 v[46:49], v[106:109], v[190:193], v[46:49]
	v_mfma_i32_16x16x64_i8 v[58:61], v[66:69], v[190:193], v[58:61]
	v_mfma_i32_16x16x64_i8 v[50:53], v[66:69], v[198:201], v[50:53]
	v_mfma_i32_16x16x64_i8 v[38:41], v[106:109], v[198:201], v[38:41]
	v_mfma_i32_16x16x64_i8 v[34:37], v[106:109], v[214:217], v[34:37]
	v_mfma_i32_16x16x64_i8 v[42:45], v[66:69], v[214:217], v[42:45]
	v_mfma_i32_16x16x64_i8 v[62:65], v[70:73], v[186:189], v[62:65]
	v_mfma_i32_16x16x64_i8 v[54:57], v[110:113], v[186:189], v[54:57]
	v_mfma_i32_16x16x64_i8 v[46:49], v[110:113], v[194:197], v[46:49]
	v_mfma_i32_16x16x64_i8 v[58:61], v[70:73], v[194:197], v[58:61]
	v_mfma_i32_16x16x64_i8 v[50:53], v[70:73], v[210:213], v[50:53]
	v_mfma_i32_16x16x64_i8 v[38:41], v[110:113], v[210:213], v[38:41]
	v_mfma_i32_16x16x64_i8 v[34:37], v[110:113], v[218:221], v[34:37]
	v_mfma_i32_16x16x64_i8 v[42:45], v[70:73], v[218:221], v[42:45]
	s_setprio 0
	s_setprio 1
	v_mfma_i32_16x16x64_i8 v[30:33], v[114:117], v[182:185], v[30:33]
	v_mfma_i32_16x16x64_i8 v[22:25], v[126:129], v[182:185], v[22:25]
	v_mfma_i32_16x16x64_i8 v[14:17], v[126:129], v[190:193], v[14:17]
	v_mfma_i32_16x16x64_i8 v[26:29], v[114:117], v[190:193], v[26:29]
	v_mfma_i32_16x16x64_i8 v[18:21], v[114:117], v[198:201], v[18:21]
	v_mfma_i32_16x16x64_i8 v[6:9], v[126:129], v[198:201], v[6:9]
	v_mfma_i32_16x16x64_i8 v[2:5], v[126:129], v[214:217], v[2:5]
	v_mfma_i32_16x16x64_i8 v[10:13], v[114:117], v[214:217], v[10:13]
	v_mfma_i32_16x16x64_i8 v[30:33], v[118:121], v[186:189], v[30:33]
	v_mfma_i32_16x16x64_i8 v[22:25], v[178:181], v[186:189], v[22:25]
	v_mfma_i32_16x16x64_i8 v[14:17], v[178:181], v[194:197], v[14:17]
	v_mfma_i32_16x16x64_i8 v[26:29], v[118:121], v[194:197], v[26:29]
	v_mfma_i32_16x16x64_i8 v[18:21], v[118:121], v[210:213], v[18:21]
	v_mfma_i32_16x16x64_i8 v[6:9], v[178:181], v[210:213], v[6:9]
	v_mfma_i32_16x16x64_i8 v[2:5], v[178:181], v[218:221], v[2:5]
	v_mfma_i32_16x16x64_i8 v[10:13], v[118:121], v[218:221], v[10:13]
	s_setprio 0
	s_barrier
	s_add_i32 s66, 0, 0x18000
	s_add_i32 s70, 0, 0x1c000
	v_add_u32_e32 v110, s66, v175
	v_add_u32_e32 v170, s70, v175
	ds_read_b128 v[66:69], v110
	ds_read_b128 v[70:73], v110 offset:1024
	ds_read_b128 v[106:109], v110 offset:2048
	ds_read_b128 v[110:113], v110 offset:3072
	ds_read_b128 v[114:117], v170
	ds_read_b128 v[118:121], v170 offset:1024
	ds_read_b128 v[126:129], v170 offset:2048
	ds_read_b128 v[178:181], v170 offset:3072
	s_add_u32 s8, vcc_lo, 0x40000
	s_addc_u32 s9, vcc_hi, 0
	s_mov_b32 m0, s80
	v_lshl_add_u64 v[226:227], s[8:9], 0, v[162:163]
	ds_read_b128 v[182:185], v177 offset:32768
	ds_read_b128 v[186:189], v177 offset:33792
	ds_read_b128 v[190:193], v177 offset:34816
	ds_read_b128 v[194:197], v177 offset:35840
	ds_read_b128 v[198:201], v177 offset:36864
	ds_read_b128 v[210:213], v177 offset:37888
	ds_read_b128 v[214:217], v177 offset:38912
	ds_read_b128 v[218:221], v177 offset:39936
	global_load_lds_dwordx4 v[226:227], off
	v_lshl_add_u64 v[226:227], s[8:9], 0, v[160:161]
	s_mov_b32 m0, s0
	s_nop 0
	global_load_lds_dwordx4 v[226:227], off
	s_waitcnt vmcnt(8)
	s_waitcnt lgkmcnt(0)
	s_barrier
	s_setprio 1
	s_waitcnt lgkmcnt(0)
	v_mfma_i32_16x16x64_i8 v[154:157], v[66:69], v[182:185], v[154:157]
	v_mfma_i32_16x16x64_i8 v[146:149], v[106:109], v[182:185], v[146:149]
	v_mfma_i32_16x16x64_i8 v[138:141], v[106:109], v[190:193], v[138:141]
	v_mfma_i32_16x16x64_i8 v[150:153], v[66:69], v[190:193], v[150:153]
	v_mfma_i32_16x16x64_i8 v[142:145], v[66:69], v[198:201], v[142:145]
	v_mfma_i32_16x16x64_i8 v[130:133], v[106:109], v[198:201], v[130:133]
	v_mfma_i32_16x16x64_i8 v[122:125], v[106:109], v[214:217], v[122:125]
	v_mfma_i32_16x16x64_i8 v[134:137], v[66:69], v[214:217], v[134:137]
	v_mfma_i32_16x16x64_i8 v[154:157], v[70:73], v[186:189], v[154:157]
	v_mfma_i32_16x16x64_i8 v[146:149], v[110:113], v[186:189], v[146:149]
	v_mfma_i32_16x16x64_i8 v[138:141], v[110:113], v[194:197], v[138:141]
	v_mfma_i32_16x16x64_i8 v[150:153], v[70:73], v[194:197], v[150:153]
	v_mfma_i32_16x16x64_i8 v[142:145], v[70:73], v[210:213], v[142:145]
	v_mfma_i32_16x16x64_i8 v[130:133], v[110:113], v[210:213], v[130:133]
	v_mfma_i32_16x16x64_i8 v[122:125], v[110:113], v[218:221], v[122:125]
	v_mfma_i32_16x16x64_i8 v[134:137], v[70:73], v[218:221], v[134:137]
	s_setprio 0
	s_setprio 1
	v_mfma_i32_16x16x64_i8 v[102:105], v[114:117], v[182:185], v[102:105]
	v_mfma_i32_16x16x64_i8 v[94:97], v[126:129], v[182:185], v[94:97]
	v_mfma_i32_16x16x64_i8 v[86:89], v[126:129], v[190:193], v[86:89]
	v_mfma_i32_16x16x64_i8 v[98:101], v[114:117], v[190:193], v[98:101]
	v_mfma_i32_16x16x64_i8 v[90:93], v[114:117], v[198:201], v[90:93]
	v_mfma_i32_16x16x64_i8 v[78:81], v[126:129], v[198:201], v[78:81]
	v_mfma_i32_16x16x64_i8 v[74:77], v[126:129], v[214:217], v[74:77]
	v_mfma_i32_16x16x64_i8 v[82:85], v[114:117], v[214:217], v[82:85]
	v_mfma_i32_16x16x64_i8 v[102:105], v[118:121], v[186:189], v[102:105]
	v_mfma_i32_16x16x64_i8 v[94:97], v[178:181], v[186:189], v[94:97]
	v_mfma_i32_16x16x64_i8 v[86:89], v[178:181], v[194:197], v[86:89]
	v_mfma_i32_16x16x64_i8 v[98:101], v[118:121], v[194:197], v[98:101]
	v_mfma_i32_16x16x64_i8 v[90:93], v[118:121], v[210:213], v[90:93]
	v_mfma_i32_16x16x64_i8 v[78:81], v[178:181], v[210:213], v[78:81]
	v_mfma_i32_16x16x64_i8 v[74:77], v[178:181], v[218:221], v[74:77]
	v_mfma_i32_16x16x64_i8 v[82:85], v[118:121], v[218:221], v[82:85]
	s_setprio 0
	s_barrier
; #define PG8_STAGE(bufoff, gbase, voff) do { _Pragma("unroll") for (int _i = 0; _i < 2; ++_i) \
;         __builtin_amdgcn_global_load_lds((const unsigned*)((const char*)(gbase) + (voff)[_i]), (PG8_LAS unsigned*)(lds + (bufoff) + ldsw + _i * 8192), 16, 0, 0); } while (0)
; #define PG8_LDA(dst, b, h) do { _Pragma("unroll") for (int m = 0; m < 4; ++m) _Pragma("unroll") for (int k = 0; k < 2; ++k) dst[m][k] = *(const PG8_LAS bf16x8*)(lds + PG8_SA(b, h) + aoff + m * 2048 + k * 1024); } while (0)
; #define PG8_LDB(dst, b, h) do { _Pragma("unroll") for (int n = 0; n < 2; ++n) _Pragma("unroll") for (int k = 0; k < 2; ++k) dst[n][k] = *(const PG8_LAS bf16x8*)(lds + PG8_SB(b, h) + boff + n * 2048 + k * 1024); } while (0)
; #define PG8_MMA(ai, bj, At, Bt) do { __builtin_amdgcn_s_setprio(1); _Pragma("unroll") for (int m = 0; m < 4; ++m) _Pragma("unroll") for (int n = 0; n < 2; ++n) _Pragma("unroll") for (int k = 0; k < 2; ++k) \
;         acc[ai][bj][m][n] = mma16<Epi::I8>(Bt[n][k], At[m][k], acc[ai][bj][m][n]); __builtin_amdgcn_s_setprio(0); } while (0)
; #define PG8_WAIT_V(n) asm volatile("s_waitcnt vmcnt(" #n ")" ::: "memory")
; template <class Epi, class Sched, bool ALIGN_EPI = false, bool SP2 = false>
; __device__ __forceinline__ void gemm_phase(PG8_LAS unsigned char* lds, const Gemm g, const Sched& S, const Epi& E) {
;     ...
;             PG8_LDB(B0, 0, 0); PG8_LDB(B1, 0, 1); PG8_SCHED; PG8_LDA(At, 0, 0); PG8_STAGE(PG8_SA(1, 1), a1 + hstep, voffA);
;             PG8_WAIT_V(8); PG8_WAIT_L(0); PG8_BAR; PG8_MMA(0, 0, At, B0); PG8_MMA(0, 1, At, B1); PG8_BAR; PG8_SCHED;
;             PG8_LDA(At, 0, 1); PG8_STAGE(PG8_SB(0, 0), b2, voffB); PG8_STAGE(PG8_SB(0, 1), b2 + hstep, voffB); PG8_STAGE(PG8_SA(0, 0), a2, voffA);
;             PG8_WAIT_V(8); PG8_WAIT_L(0); PG8_BAR; PG8_MMA(1, 0, At, B0); PG8_MMA(1, 1, At, B1); PG8_BAR; PG8_SCHED;
;             PG8_LDB(B0, 1, 0); PG8_LDB(B1, 1, 1); PG8_SCHED; PG8_LDA(At, 1, 0); PG8_STAGE(PG8_SA(0, 1), a2 + hstep, voffA);
;             PG8_WAIT_V(8); PG8_WAIT_L(0); PG8_BAR; PG8_MMA(0, 0, At, B0); PG8_MMA(0, 1, At, B1); PG8_BAR; PG8_SCHED;
;             PG8_LDA(At, 1, 1); PG8_STAGE(PG8_SB(1, 0), b3, voffB); PG8_STAGE(PG8_SB(1, 1), b3 + hstep, voffB); PG8_STAGE(PG8_SA(1, 0), a3, voffA);
;             PG8_WAIT_V(8); PG8_WAIT_L(0); PG8_BAR; PG8_MMA(1, 0, At, B0); PG8_MMA(1, 1, At, B1); PG8_BAR; PG8_SCHED;
	s_add_i32 s8, s66, s81
	v_lshl_add_u64 v[168:169], v[168:169], 0, s[92:93]
	s_mov_b32 m0, s8
	ds_read_b128 v[182:185], v177 offset:49152
	ds_read_b128 v[186:189], v177 offset:50176
	ds_read_b128 v[190:193], v177 offset:51200
	ds_read_b128 v[194:197], v177 offset:52224
	ds_read_b128 v[198:201], v177 offset:53248
	ds_read_b128 v[210:213], v177 offset:54272
	ds_read_b128 v[214:217], v177 offset:55296
	ds_read_b128 v[218:221], v177 offset:56320
	global_load_lds_dwordx4 v[168:169], off
	s_add_i32 m0, s8, 0x2000
	s_add_u32 s8, s96, 0x40080
	v_lshl_add_u64 v[168:169], v[206:207], 0, s[92:93]
	s_addc_u32 s9, s97, 0
	s_add_i32 s66, s70, s81
	global_load_lds_dwordx4 v[168:169], off
	v_lshl_add_u64 v[168:169], s[8:9], 0, v[0:1]
	s_mov_b32 m0, s66
	s_nop 0
	global_load_lds_dwordx4 v[168:169], off
	v_lshl_add_u64 v[168:169], s[8:9], 0, v[158:159]
	s_add_i32 m0, s66, 0x2000
	s_nop 0
	global_load_lds_dwordx4 v[168:169], off
	v_lshl_add_u64 v[168:169], v[222:223], 0, s[92:93]
	s_mov_b32 m0, s13
	s_nop 0
	global_load_lds_dwordx4 v[168:169], off
	v_lshl_add_u64 v[168:169], v[224:225], 0, s[92:93]
	s_mov_b32 m0, s12
	s_nop 0
	global_load_lds_dwordx4 v[168:169], off
	s_waitcnt vmcnt(8)
	s_waitcnt lgkmcnt(0)
	s_barrier
	s_setprio 1
	s_waitcnt lgkmcnt(0)
	v_mfma_i32_16x16x64_i8 v[62:65], v[66:69], v[182:185], v[62:65]
	v_mfma_i32_16x16x64_i8 v[54:57], v[106:109], v[182:185], v[54:57]
	v_mfma_i32_16x16x64_i8 v[46:49], v[106:109], v[190:193], v[46:49]
	v_mfma_i32_16x16x64_i8 v[58:61], v[66:69], v[190:193], v[58:61]
	v_mfma_i32_16x16x64_i8 v[50:53], v[66:69], v[198:201], v[50:53]
	v_mfma_i32_16x16x64_i8 v[38:41], v[106:109], v[198:201], v[38:41]
	v_mfma_i32_16x16x64_i8 v[34:37], v[106:109], v[214:217], v[34:37]
	v_mfma_i32_16x16x64_i8 v[42:45], v[66:69], v[214:217], v[42:45]
	v_mfma_i32_16x16x64_i8 v[62:65], v[70:73], v[186:189], v[62:65]
	v_mfma_i32_16x16x64_i8 v[54:57], v[110:113], v[186:189], v[54:57]
	v_mfma_i32_16x16x64_i8 v[46:49], v[110:113], v[194:197], v[46:49]
	v_mfma_i32_16x16x64_i8 v[58:61], v[70:73], v[194:197], v[58:61]
	v_mfma_i32_16x16x64_i8 v[50:53], v[70:73], v[210:213], v[50:53]
	v_mfma_i32_16x16x64_i8 v[38:41], v[110:113], v[210:213], v[38:41]
	v_mfma_i32_16x16x64_i8 v[34:37], v[110:113], v[218:221], v[34:37]
	v_mfma_i32_16x16x64_i8 v[42:45], v[70:73], v[218:221], v[42:45]
	s_setprio 0
	s_setprio 1
	v_mfma_i32_16x16x64_i8 v[30:33], v[114:117], v[182:185], v[30:33]
	v_mfma_i32_16x16x64_i8 v[22:25], v[126:129], v[182:185], v[22:25]
	v_mfma_i32_16x16x64_i8 v[14:17], v[126:129], v[190:193], v[14:17]
	v_mfma_i32_16x16x64_i8 v[26:29], v[114:117], v[190:193], v[26:29]
	v_mfma_i32_16x16x64_i8 v[18:21], v[114:117], v[198:201], v[18:21]
	v_mfma_i32_16x16x64_i8 v[6:9], v[126:129], v[198:201], v[6:9]
	v_mfma_i32_16x16x64_i8 v[2:5], v[126:129], v[214:217], v[2:5]
	v_mfma_i32_16x16x64_i8 v[10:13], v[114:117], v[214:217], v[10:13]
	v_mfma_i32_16x16x64_i8 v[30:33], v[118:121], v[186:189], v[30:33]
	v_mfma_i32_16x16x64_i8 v[22:25], v[178:181], v[186:189], v[22:25]
	v_mfma_i32_16x16x64_i8 v[14:17], v[178:181], v[194:197], v[14:17]
	v_mfma_i32_16x16x64_i8 v[26:29], v[118:121], v[194:197], v[26:29]
	v_mfma_i32_16x16x64_i8 v[18:21], v[118:121], v[210:213], v[18:21]
	v_mfma_i32_16x16x64_i8 v[6:9], v[178:181], v[210:213], v[6:9]
	v_mfma_i32_16x16x64_i8 v[2:5], v[178:181], v[218:221], v[2:5]
	v_mfma_i32_16x16x64_i8 v[10:13], v[118:121], v[218:221], v[10:13]
	s_setprio 0
	s_barrier
	s_add_i32 s10, s10, 2
	s_add_u32 s69, s69, 0x100
	s_addc_u32 s68, s68, 0
	s_cmp_gt_u32 s10, 13
	s_mov_b64 s[8:9], s[84:85]
	s_cbranch_scc0 .LBB0_291
